# v7 + ret_kv staging loads hoisted (8 in flight, counted waits)
# speedup vs baseline: 1.0107x; 1.0014x over previous
; __device__ __forceinline__ float bflo(unsigned w) { return __uint_as_float(w << 16); }
; __device__ __forceinline__ float bfhi(unsigned w) { return __uint_as_float(w & 0xffff0000u); }
; __device__ __forceinline__ unsigned pk2(float lo, float hi) { return pg8::cvt_pk_bf16(lo, hi); }
; __device__ __forceinline__ void ret_kv_unit(LAS unsigned char* lds, const bf16* Z, bf16* RT, int h, int n, int tid) {
;     ...
;     const bf16* zb = Z + (size_t)(n * 128) * NIN + h * 128;
; #pragma unroll
;     for (int i = 0; i < 4; ++i) {
;         const int kq = i * 8 + wid, c8 = kq >> 1, t = (kq & 1) * 64 + lane;
;         v4u kv = *(const v4u*)(zb + (size_t)t * NIN + ZKR + c8 * 8);
;         const v4u vv = *(const v4u*)(zb + (size_t)t * NIN + ZVR + c8 * 8);
;         const float zt = exp2f((float)(127 - t) * l2g);
;         kv.x = pk2(bflo(kv.x) * zt, bfhi(kv.x) * zt); kv.y = pk2(bflo(kv.y) * zt, bfhi(kv.y) * zt); kv.z = pk2(bflo(kv.z) * zt, bfhi(kv.z) * zt); kv.w = pk2(bflo(kv.w) * zt, bfhi(kv.w) * zt);
;         lds_scatter8(KT, c8 * 8, t, kv); lds_scatter8(VT, c8 * 8, t, vv);
;     }
.LBB0_156:
	s_ashr_i32 s5, s3, 7
	v_cvt_f32_i32_e32 v0, s5
	s_and_b32 s10, s3, 0x7f
	s_mul_i32 s10, s10, 0x2c0000
	v_sub_f32_e32 v0, 0xc0a00000, v0
	v_cmp_gt_f32_e32 vcc, s96, v0
	s_and_b64 s[8:9], vcc, exec
	s_cselect_b32 s5, 0xffffffc0, 0
	v_cndmask_b32_e32 v2, 0, v234, vcc
	v_add_f32_e32 v0, v0, v2
	v_exp_f32_e32 v0, v0
	s_nop 0
	v_ldexp_f32 v0, v0, s5
	v_sub_f32_e32 v0, 1.0, v0
	v_log_f32_e32 v0, v0
	s_add_u32 s5, s16, s10
	s_addc_u32 s10, s17, 0
	s_and_b32 s8, s3, 0xffffff80
	s_ashr_i32 s9, s8, 31
	s_lshl_b64 s[8:9], s[8:9], 1
	s_add_u32 s8, s5, s8
	v_mul_f32_e32 v4, v0, v56
	s_addc_u32 s9, s10, s9
	v_cmp_gt_f32_e32 vcc, s96, v4
	v_lshl_add_u64 v[2:3], s[8:9], 0, v[192:193]
	v_lshl_add_u64 v[2:3], v[18:19], 1, v[2:3]
	v_cndmask_b32_e32 v4, 0, v234, vcc
	v_fmac_f32_e32 v4, v0, v56
	v_exp_f32_e32 v0, v4
	v_cndmask_b32_e32 v4, 0, v235, vcc
	v_add_co_u32_e32 v10, vcc, s93, v2
	v_ldexp_f32 v0, v0, v4
	s_nop 0
	v_addc_co_u32_e32 v11, vcc, 0, v3, vcc
	v_lshl_add_u64 v[4:5], v[2:3], 0, s[14:15]
	v_lshl_add_u64 v[2:3], v[2:3], 0, s[12:13]
	global_load_dwordx4 v[104:107], v[10:11], off
	global_load_dwordx4 v[108:111], v[10:11], off offset:2048
	global_load_dwordx4 v[112:115], v[4:5], off offset:64
	global_load_dwordx4 v[116:119], v[2:3], off offset:64
	global_load_dwordx4 v[120:123], v[4:5], off offset:128
	global_load_dwordx4 v[124:127], v[2:3], off offset:128
	global_load_dwordx4 v[128:131], v[4:5], off offset:192
	global_load_dwordx4 v[132:135], v[2:3], off offset:192
	s_add_i32 s3, s3, s2
	s_waitcnt vmcnt(7)
	v_lshlrev_b32_e32 v12, 16, v104
	v_and_b32_e32 v13, 0xffff0000, v104
	v_lshlrev_b32_e32 v6, 16, v105
	v_and_b32_e32 v7, 0xffff0000, v105
	v_pk_mul_f32 v[12:13], v[0:1], v[12:13] op_sel_hi:[0, 1]
	v_pk_mul_f32 v[6:7], v[0:1], v[6:7] op_sel_hi:[0, 1]
	v_cvt_pk_bf16_f32 v12, v12, v13
	v_cvt_pk_bf16_f32 v13, v6, v7
	v_lshlrev_b32_e32 v6, 16, v106
	v_and_b32_e32 v7, 0xffff0000, v106
	v_pk_mul_f32 v[6:7], v[0:1], v[6:7] op_sel_hi:[0, 1]
	v_cvt_pk_bf16_f32 v8, v6, v7
	v_lshlrev_b32_e32 v6, 16, v107
	v_and_b32_e32 v7, 0xffff0000, v107
	v_pk_mul_f32 v[6:7], v[0:1], v[6:7] op_sel_hi:[0, 1]
	v_cvt_pk_bf16_f32 v6, v6, v7
	ds_write_b16 v57, v12 offset:34816
	ds_write_b16_d16_hi v57, v12 offset:35088
	ds_write_b16 v57, v13 offset:35360
	ds_write_b16_d16_hi v57, v13 offset:35632
	ds_write_b16 v57, v8 offset:35904
	ds_write_b16_d16_hi v57, v8 offset:36176
	ds_write_b16 v57, v6 offset:36448
	ds_write_b16_d16_hi v57, v6 offset:36720
	s_waitcnt vmcnt(6)
	ds_write_b16 v57, v108
	ds_write_b16_d16_hi v57, v108 offset:272
	ds_write_b16 v57, v109 offset:544
	ds_write_b16_d16_hi v57, v109 offset:816
	ds_write_b16 v57, v110 offset:1088
	ds_write_b16_d16_hi v57, v110 offset:1360
	ds_write_b16 v57, v111 offset:1632
	ds_write_b16_d16_hi v57, v111 offset:1904
	s_waitcnt vmcnt(5)
	v_lshlrev_b32_e32 v10, 16, v112
	v_and_b32_e32 v11, 0xffff0000, v112
	v_lshlrev_b32_e32 v6, 16, v113
	v_and_b32_e32 v7, 0xffff0000, v113
	v_pk_mul_f32 v[10:11], v[0:1], v[10:11] op_sel_hi:[0, 1]
	v_pk_mul_f32 v[6:7], v[0:1], v[6:7] op_sel_hi:[0, 1]
	v_cvt_pk_bf16_f32 v10, v10, v11
	v_cvt_pk_bf16_f32 v11, v6, v7
	v_lshlrev_b32_e32 v6, 16, v114
	v_and_b32_e32 v7, 0xffff0000, v114
	v_pk_mul_f32 v[6:7], v[0:1], v[6:7] op_sel_hi:[0, 1]
	v_cvt_pk_bf16_f32 v8, v6, v7
	v_lshlrev_b32_e32 v6, 16, v115
	v_and_b32_e32 v7, 0xffff0000, v115
	v_pk_mul_f32 v[6:7], v[0:1], v[6:7] op_sel_hi:[0, 1]
	v_cvt_pk_bf16_f32 v6, v6, v7
	ds_write_b16 v57, v10 offset:43520
	ds_write_b16_d16_hi v57, v10 offset:43792
	ds_write_b16 v57, v11 offset:44064
	ds_write_b16_d16_hi v57, v11 offset:44336
	ds_write_b16 v57, v8 offset:44608
	ds_write_b16_d16_hi v57, v8 offset:44880
	ds_write_b16 v57, v6 offset:45152
	ds_write_b16_d16_hi v57, v6 offset:45424
	s_waitcnt vmcnt(4)
	ds_write_b16 v57, v116 offset:8704
	ds_write_b16_d16_hi v57, v116 offset:8976
	ds_write_b16 v57, v117 offset:9248
	ds_write_b16_d16_hi v57, v117 offset:9520
	ds_write_b16 v57, v118 offset:9792
	ds_write_b16_d16_hi v57, v118 offset:10064
	ds_write_b16 v57, v119 offset:10336
	ds_write_b16_d16_hi v57, v119 offset:10608
	s_waitcnt vmcnt(3)
	v_lshlrev_b32_e32 v10, 16, v120
	v_and_b32_e32 v11, 0xffff0000, v120
	v_lshlrev_b32_e32 v6, 16, v121
	v_and_b32_e32 v7, 0xffff0000, v121
	v_pk_mul_f32 v[10:11], v[0:1], v[10:11] op_sel_hi:[0, 1]
	v_pk_mul_f32 v[6:7], v[0:1], v[6:7] op_sel_hi:[0, 1]
	v_cvt_pk_bf16_f32 v10, v10, v11
	v_cvt_pk_bf16_f32 v11, v6, v7
	v_lshlrev_b32_e32 v6, 16, v122
	v_and_b32_e32 v7, 0xffff0000, v122
	v_pk_mul_f32 v[6:7], v[0:1], v[6:7] op_sel_hi:[0, 1]
	v_cvt_pk_bf16_f32 v8, v6, v7
	v_lshlrev_b32_e32 v6, 16, v123
	v_and_b32_e32 v7, 0xffff0000, v123
	v_pk_mul_f32 v[6:7], v[0:1], v[6:7] op_sel_hi:[0, 1]
	v_cvt_pk_bf16_f32 v6, v6, v7
	ds_write_b16 v57, v10 offset:52224
	ds_write_b16_d16_hi v57, v10 offset:52496
	ds_write_b16 v57, v11 offset:52768
	ds_write_b16_d16_hi v57, v11 offset:53040
	ds_write_b16 v57, v8 offset:53312
	ds_write_b16_d16_hi v57, v8 offset:53584
	ds_write_b16 v57, v6 offset:53856
	ds_write_b16_d16_hi v57, v6 offset:54128
	s_waitcnt vmcnt(2)
	ds_write_b16 v57, v124 offset:17408
	ds_write_b16_d16_hi v57, v124 offset:17680
	ds_write_b16 v57, v125 offset:17952
	ds_write_b16_d16_hi v57, v125 offset:18224
	ds_write_b16 v57, v126 offset:18496
	ds_write_b16_d16_hi v57, v126 offset:18768
	ds_write_b16 v57, v127 offset:19040
	ds_write_b16_d16_hi v57, v127 offset:19312
	s_waitcnt vmcnt(1)
	v_lshlrev_b32_e32 v8, 16, v128
	v_and_b32_e32 v9, 0xffff0000, v128
	v_lshlrev_b32_e32 v4, 16, v129
	v_and_b32_e32 v5, 0xffff0000, v129
	v_pk_mul_f32 v[8:9], v[0:1], v[8:9] op_sel_hi:[0, 1]
	v_pk_mul_f32 v[4:5], v[0:1], v[4:5] op_sel_hi:[0, 1]
	v_cvt_pk_bf16_f32 v8, v8, v9
	v_cvt_pk_bf16_f32 v9, v4, v5
	v_lshlrev_b32_e32 v4, 16, v130
	v_and_b32_e32 v5, 0xffff0000, v130
	v_pk_mul_f32 v[4:5], v[0:1], v[4:5] op_sel_hi:[0, 1]
	v_cvt_pk_bf16_f32 v6, v4, v5
	v_lshlrev_b32_e32 v4, 16, v131
	v_and_b32_e32 v5, 0xffff0000, v131
	v_pk_mul_f32 v[4:5], v[0:1], v[4:5] op_sel_hi:[0, 1]
	v_cvt_pk_bf16_f32 v0, v4, v5
	ds_write_b16 v57, v8 offset:60928
	ds_write_b16_d16_hi v57, v8 offset:61200
	ds_write_b16 v57, v9 offset:61472
	ds_write_b16_d16_hi v57, v9 offset:61744
	ds_write_b16 v57, v6 offset:62016
	ds_write_b16_d16_hi v57, v6 offset:62288
	ds_write_b16 v57, v0 offset:62560
	ds_write_b16_d16_hi v57, v0 offset:62832
	s_waitcnt vmcnt(0)
	ds_write_b16 v57, v132 offset:26112
	ds_write_b16_d16_hi v57, v132 offset:26384
	ds_write_b16 v57, v133 offset:26656
	ds_write_b16_d16_hi v57, v133 offset:26928
	ds_write_b16 v57, v134 offset:27200
	ds_write_b16_d16_hi v57, v134 offset:27472
	ds_write_b16 v57, v135 offset:27744
	ds_write_b16_d16_hi v57, v135 offset:28016
	s_waitcnt lgkmcnt(0)
	s_barrier
; #define LAS __attribute__((address_space(3)))
; __device__ __forceinline__ unsigned short f2bf1(float f) { return (unsigned short)(pk2(f, 0.f) & 0xffffu); }
; template <int MI, int NJ> __device__ __forceinline__ void mm_nt(f32x4 (&acc)[MI][NJ], const LAS unsigned char* A, const LAS unsigned char* B, int m0, int n0, int fr, int fq) {
; #pragma unroll
;     for (int kk = 0; kk < 4; ++kk) {
;         bf16x8 a[MI], b[NJ];
; #pragma unroll
;         for (int mi = 0; mi < MI; ++mi) a[mi] = *(const LAS bf16x8*)(A + (m0 + 16 * mi + fr) * TP + kk * 64 + fq * 16);
; #pragma unroll
;         for (int nj = 0; nj < NJ; ++nj) b[nj] = *(const LAS bf16x8*)(B + (n0 + 16 * nj + fr) * TP + kk * 64 + fq * 16);
; #pragma unroll
;         for (int mi = 0; mi < MI; ++mi)
; #pragma unroll
;             for (int nj = 0; nj < NJ; ++nj) acc[mi][nj] = __builtin_amdgcn_mfma_f32_16x16x32_bf16(a[mi], b[nj], acc[mi][nj], 0, 0, 0);
;     }
; }
; __device__ __forceinline__ void ret_kv_unit(LAS unsigned char* lds, const bf16* Z, bf16* RT, int h, int n, int tid) {
;     ...
;     f32x4 acc[2][4];
; #pragma unroll
;     for (int mi = 0; mi < 2; ++mi)
; #pragma unroll
;         for (int nj = 0; nj < 4; ++nj) acc[mi][nj] = (f32x4){0.f, 0.f, 0.f, 0.f};
;     mm_nt<2, 4>(acc, VT, KT, 32 * wm, 64 * wn, fr, fq);
;     bf16* rt = RT + (size_t)(h * 128 + n) * 16384;
; #pragma unroll
;     for (int mi = 0; mi < 2; ++mi)
; #pragma unroll
;         for (int nj = 0; nj < 4; ++nj)
; #pragma unroll
;             for (int e = 0; e < 4; ++e) rt[(32 * wm + 16 * mi + 4 * fq + e) * 128 + 64 * wn + 16 * nj + fr] = f2bf1(acc[mi][nj][e]);
;     __syncthreads();
	ds_read_b128 v[2:5], v58
	ds_read_b128 v[6:9], v58 offset:4352
	ds_read_b128 v[10:13], v59 offset:34816
	ds_read_b128 v[14:17], v59 offset:39168
	ds_read_b128 v[60:63], v59 offset:43520
	ds_read_b128 v[64:67], v59 offset:47872
	s_waitcnt lgkmcnt(3)
	v_mfma_f32_16x16x32_bf16 v[68:71], v[2:5], v[10:13], 0
	s_waitcnt lgkmcnt(2)
	v_mfma_f32_16x16x32_bf16 v[72:75], v[2:5], v[14:17], 0
	s_waitcnt lgkmcnt(1)
	v_mfma_f32_16x16x32_bf16 v[76:79], v[2:5], v[60:63], 0
	s_waitcnt lgkmcnt(0)
	v_mfma_f32_16x16x32_bf16 v[2:5], v[2:5], v[64:67], 0
	v_mfma_f32_16x16x32_bf16 v[10:13], v[6:9], v[10:13], 0
	v_mfma_f32_16x16x32_bf16 v[14:17], v[6:9], v[14:17], 0
	v_mfma_f32_16x16x32_bf16 v[60:63], v[6:9], v[60:63], 0
	v_mfma_f32_16x16x32_bf16 v[6:9], v[6:9], v[64:67], 0
	ds_read_b128 v[64:67], v58 offset:64
	ds_read_b128 v[80:83], v58 offset:4416
	ds_read_b128 v[84:87], v59 offset:34880
	ds_read_b128 v[88:91], v59 offset:39232
	ds_read_b128 v[92:95], v59 offset:43584
	ds_read_b128 v[96:99], v59 offset:47936
	s_waitcnt lgkmcnt(3)
	v_mfma_f32_16x16x32_bf16 v[68:71], v[64:67], v[84:87], v[68:71]
	s_waitcnt lgkmcnt(2)
	v_mfma_f32_16x16x32_bf16 v[72:75], v[64:67], v[88:91], v[72:75]
	s_waitcnt lgkmcnt(1)
	v_mfma_f32_16x16x32_bf16 v[76:79], v[64:67], v[92:95], v[76:79]
	s_waitcnt lgkmcnt(0)
	v_mfma_f32_16x16x32_bf16 v[2:5], v[64:67], v[96:99], v[2:5]
	v_mfma_f32_16x16x32_bf16 v[10:13], v[80:83], v[84:87], v[10:13]
	v_mfma_f32_16x16x32_bf16 v[14:17], v[80:83], v[88:91], v[14:17]
	v_mfma_f32_16x16x32_bf16 v[60:63], v[80:83], v[92:95], v[60:63]
	v_mfma_f32_16x16x32_bf16 v[6:9], v[80:83], v[96:99], v[6:9]
	ds_read_b128 v[64:67], v58 offset:128
	ds_read_b128 v[80:83], v58 offset:4480
	ds_read_b128 v[84:87], v59 offset:34944
	ds_read_b128 v[88:91], v59 offset:39296
	ds_read_b128 v[92:95], v59 offset:43648
	ds_read_b128 v[96:99], v59 offset:48000
	s_waitcnt lgkmcnt(3)
	v_mfma_f32_16x16x32_bf16 v[68:71], v[64:67], v[84:87], v[68:71]
	s_waitcnt lgkmcnt(2)
	v_mfma_f32_16x16x32_bf16 v[72:75], v[64:67], v[88:91], v[72:75]
	s_waitcnt lgkmcnt(1)
	v_mfma_f32_16x16x32_bf16 v[76:79], v[64:67], v[92:95], v[76:79]
	s_waitcnt lgkmcnt(0)
	v_mfma_f32_16x16x32_bf16 v[2:5], v[64:67], v[96:99], v[2:5]
	v_mfma_f32_16x16x32_bf16 v[10:13], v[80:83], v[84:87], v[10:13]
	v_mfma_f32_16x16x32_bf16 v[64:67], v[80:83], v[88:91], v[14:17]
	v_mfma_f32_16x16x32_bf16 v[60:63], v[80:83], v[92:95], v[60:63]
	v_mfma_f32_16x16x32_bf16 v[80:83], v[80:83], v[96:99], v[6:9]
	s_nop 2
	ds_read_b128 v[6:9], v58 offset:192
	ds_read_b128 v[84:87], v58 offset:4544
	ds_read_b128 v[14:17], v59 offset:35008
	ds_read_b128 v[88:91], v59 offset:39360
	ds_read_b128 v[92:95], v59 offset:43712
	ds_read_b128 v[96:99], v59 offset:48064
	s_waitcnt lgkmcnt(3)
	v_mfma_f32_16x16x32_bf16 v[68:71], v[6:9], v[14:17], v[68:71]
	s_waitcnt lgkmcnt(2)
	v_mfma_f32_16x16x32_bf16 v[72:75], v[6:9], v[88:91], v[72:75]
	s_waitcnt lgkmcnt(1)
	v_mfma_f32_16x16x32_bf16 v[76:79], v[6:9], v[92:95], v[76:79]
	s_nop 3
	v_cvt_pk_bf16_f32 v0, v68, s0
	s_waitcnt lgkmcnt(0)
	v_mfma_f32_16x16x32_bf16 v[100:103], v[6:9], v[96:99], v[2:5]
	v_mfma_f32_16x16x32_bf16 v[6:9], v[84:87], v[92:95], v[60:63]
	s_nop 2
	v_lshl_add_u64 v[60:61], s[0:1], 0, v[50:51]
	global_store_short v[60:61], v0, off
	v_cvt_pk_bf16_f32 v0, v69, s0
	v_lshl_add_u64 v[60:61], s[0:1], 0, v[46:47]
	global_store_short v[60:61], v0, off offset:-256
	v_cvt_pk_bf16_f32 v0, v70, s0
	global_store_short v[60:61], v0, off
	v_cvt_pk_bf16_f32 v0, v71, s0
	global_store_short v[60:61], v0, off offset:256
	v_cvt_pk_bf16_f32 v0, v72, s0
	global_store_short v[60:61], v0, off offset:-480
	v_cvt_pk_bf16_f32 v0, v73, s0
	global_store_short v[60:61], v0, off offset:-224
	v_cvt_pk_bf16_f32 v0, v74, s0
	global_store_short v[60:61], v0, off offset:32
	v_cvt_pk_bf16_f32 v0, v75, s0
	global_store_short v[60:61], v0, off offset:288
	v_cvt_pk_bf16_f32 v0, v76, s0
	global_store_short v[60:61], v0, off offset:-448
	v_cvt_pk_bf16_f32 v0, v77, s0
	global_store_short v[60:61], v0, off offset:-192
	v_cvt_pk_bf16_f32 v0, v78, s0
	global_store_short v[60:61], v0, off offset:64
	v_cvt_pk_bf16_f32 v0, v79, s0
	v_mfma_f32_16x16x32_bf16 v[14:17], v[84:87], v[14:17], v[10:13]
	global_store_short v[60:61], v0, off offset:320
	v_cvt_pk_bf16_f32 v0, v100, s0
	global_store_short v[60:61], v0, off offset:-416
	v_cvt_pk_bf16_f32 v0, v101, s0
	global_store_short v[60:61], v0, off offset:-160
	v_cvt_pk_bf16_f32 v0, v102, s0
	global_store_short v[60:61], v0, off offset:96
	v_cvt_pk_bf16_f32 v0, v103, s0
	v_mfma_f32_16x16x32_bf16 v[10:13], v[84:87], v[88:91], v[64:67]
	global_store_short v[60:61], v0, off offset:352
	v_cvt_pk_bf16_f32 v0, v14, s0
	v_lshl_add_u64 v[60:61], s[0:1], 0, v[52:53]
	global_store_short v[60:61], v0, off
	v_cvt_pk_bf16_f32 v0, v15, s0
	v_lshl_add_u64 v[14:15], s[0:1], 0, v[54:55]
	global_store_short v[14:15], v0, off
	v_cvt_pk_bf16_f32 v0, v16, s0
	v_lshl_add_u64 v[14:15], s[0:1], 0, v[48:49]
	global_store_short v[14:15], v0, off
	v_cvt_pk_bf16_f32 v0, v17, s0
	v_lshl_add_u64 v[14:15], s[0:1], 0, v[44:45]
	global_store_short v[14:15], v0, off
	v_cvt_pk_bf16_f32 v0, v10, s0
	v_lshl_add_u64 v[14:15], s[0:1], 0, v[42:43]
	global_store_short v[14:15], v0, off
	v_cvt_pk_bf16_f32 v0, v11, s0
	v_lshl_add_u64 v[10:11], s[0:1], 0, v[40:41]
	global_store_short v[10:11], v0, off
	v_cvt_pk_bf16_f32 v0, v12, s0
	v_lshl_add_u64 v[10:11], s[0:1], 0, v[38:39]
	global_store_short v[10:11], v0, off
	v_cvt_pk_bf16_f32 v0, v13, s0
	v_lshl_add_u64 v[10:11], s[0:1], 0, v[36:37]
	v_mfma_f32_16x16x32_bf16 v[2:5], v[84:87], v[96:99], v[80:83]
	global_store_short v[10:11], v0, off
	v_cvt_pk_bf16_f32 v0, v6, s0
	v_lshl_add_u64 v[10:11], s[0:1], 0, v[34:35]
	global_store_short v[10:11], v0, off
	v_cvt_pk_bf16_f32 v0, v7, s0
	v_lshl_add_u64 v[6:7], s[0:1], 0, v[32:33]
	global_store_short v[6:7], v0, off
	v_cvt_pk_bf16_f32 v0, v8, s0
	v_lshl_add_u64 v[6:7], s[0:1], 0, v[30:31]
	global_store_short v[6:7], v0, off
	v_cvt_pk_bf16_f32 v0, v9, s0
	v_lshl_add_u64 v[6:7], s[0:1], 0, v[28:29]
	global_store_short v[6:7], v0, off
	v_cvt_pk_bf16_f32 v0, v2, s0
	v_lshl_add_u64 v[6:7], s[0:1], 0, v[26:27]
	global_store_short v[6:7], v0, off
	v_cvt_pk_bf16_f32 v0, v3, s0
	v_lshl_add_u64 v[2:3], s[0:1], 0, v[24:25]
	global_store_short v[2:3], v0, off
	v_cvt_pk_bf16_f32 v0, v4, s0
	v_lshl_add_u64 v[2:3], s[0:1], 0, v[22:23]
	global_store_short v[2:3], v0, off
	v_cvt_pk_bf16_f32 v0, v5, s0
	v_lshl_add_u64 v[2:3], s[0:1], 0, v[20:21]
	s_add_u32 s0, s0, s6
	s_addc_u32 s1, s1, s7
	s_cmpk_gt_i32 s3, 0x3ff
	global_store_short v[2:3], v0, off
	s_barrier
	s_cbranch_scc0 .LBB0_156
